# v26 + norm (phase +5) two-row loop: second row's loads issued before waiting for the first row's
# speedup vs baseline: 1.0043x; 1.0043x over previous
; __device__ __forceinline__ void unpack8(u32x4 w, f32x4& a, f32x4& b) { a = (f32x4){bf_lo(w.x), bf_hi(w.x), bf_lo(w.y), bf_hi(w.y)}; b = (f32x4){bf_lo(w.z), bf_hi(w.z), bf_lo(w.w), bf_hi(w.w)}; }
; template <int NR>
; __device__ __forceinline__ void norm_prompt_rows(const Args& args, const float* gpost, bool last, bool want_q, const int (&rows)[NR], int lane) {
;     ...
;     for (int r = 0; r < NR; ++r) {
;         part[r] = lane < 32 ? SSY[(size_t)rows[r] * 32 + lane] : 0.f; xs[r] = RS[rows[r]];
; #pragma unroll
;         for (int j = 0; j < 4; ++j) { xq[r][j] = __builtin_nontemporal_load((const u32x4*)(XB + (size_t)rows[r] * DM + j * 512 + lane * 8)); yq[r][j] = __builtin_nontemporal_load((const u32x4*)(Y + (size_t)rows[r] * DM + j * 512 + lane * 8)); }
;     }
; #pragma unroll
;     for (int o = 1; o < 64; o <<= 1)
; #pragma unroll
;         for (int r = 0; r < NR; ++r) part[r] += __shfl_xor(part[r], o);
; #pragma unroll
;     for (int r = 0; r < NR; ++r) { rstd[r] = __builtin_amdgcn_rsqf(part[r] * (1.0f / DM) + EPS); ss[r] = 0.f; }
;     f32x4 n0[NR][4], n1[NR][4];
; #pragma unroll
;     for (int j = 0; j < 4; ++j) {
;         const int c = j * 512 + lane * 8;
;         const f32x4 g0 = *(const f32x4*)(gpost + c), g1 = *(const f32x4*)(gpost + c + 4);
; #pragma unroll
;         for (int r = 0; r < NR; ++r) {
;             f32x4 x0, x1, y0, y1; unpack8(xq[r][j], x0, x1); unpack8(yq[r][j], y0, y1);
;             const f32x4 a = x0 * xs[r] + y0 * rstd[r] * g0, b = x1 * xs[r] + y1 * rstd[r] * g1;
;             n0[r][j] = a; n1[r][j] = b;
;             ss[r] += (a[0] * a[0] + a[1] * a[1]) + (a[2] * a[2] + a[3] * a[3]) + (b[0] * b[0] + b[1] * b[1]) + (b[2] * b[2] + b[3] * b[3]);
;         }
;     }
.LBB0_1244:
	s_or_b64 exec, exec, s[16:17]
	s_mov_b64 s[2:3], 0x23a00000
	v_lshl_add_u64 v[102:103], v[2:3], 0, s[2:3]
	s_mov_b64 s[2:3], 0x23a00400
	v_lshl_add_u64 v[100:101], v[2:3], 0, s[2:3]
	s_mov_b64 s[2:3], 0x23a00800
	v_lshl_add_u64 v[98:99], v[2:3], 0, s[2:3]
	s_mov_b64 s[2:3], 0x23a00c00
	v_lshl_add_u64 v[96:97], v[2:3], 0, s[2:3]
	s_lshl_b64 s[16:17], s[0:1], 2
	s_add_u32 s26, s5, s16
	s_addc_u32 s27, s14, s17
	s_lshl_b64 s[2:3], s[0:1], 12
	v_lshl_add_u64 v[94:95], v[74:75], 0, s[2:3]
	v_lshl_add_u64 v[2:3], v[76:77], 0, s[2:3]
	global_load_dword v110, v131, s[26:27]
	global_load_dwordx4 v[62:65], v[94:95], off nt
	global_load_dwordx4 v[54:57], v[2:3], off nt
	global_load_dwordx4 v[46:49], v[94:95], off offset:1024 nt
	global_load_dwordx4 v[42:45], v[2:3], off offset:1024 nt
	global_load_dwordx4 v[30:33], v[94:95], off offset:2048 nt
	global_load_dwordx4 v[26:29], v[2:3], off offset:2048 nt
	global_load_dwordx4 v[6:9], v[94:95], off offset:3072 nt
	s_nop 0
	global_load_dwordx4 v[2:5], v[2:3], off offset:3072 nt
	s_waitcnt vmcnt(18)
	ds_bpermute_b32 v68, v109, v67
	s_waitcnt lgkmcnt(0)
	v_add_f32_e32 v67, v67, v68
	s_waitcnt vmcnt(9)
	ds_bpermute_b32 v68, v109, v66
	s_waitcnt lgkmcnt(0)
	v_add_f32_e32 v66, v66, v68
	ds_bpermute_b32 v68, v111, v67
	s_waitcnt lgkmcnt(0)
	v_add_f32_e32 v67, v67, v68
	ds_bpermute_b32 v68, v111, v66
	s_waitcnt lgkmcnt(0)
	v_add_f32_e32 v66, v66, v68
	ds_bpermute_b32 v68, v113, v67
	v_lshlrev_b32_e32 v122, 16, v50
	v_and_b32_e32 v123, 0xffff0000, v50
	v_lshlrev_b32_e32 v50, 16, v51
	v_and_b32_e32 v51, 0xffff0000, v51
	s_waitcnt lgkmcnt(0)
	v_add_f32_e32 v67, v67, v68
	ds_bpermute_b32 v68, v113, v66
	v_lshlrev_b32_e32 v104, 16, v58
	v_and_b32_e32 v105, 0xffff0000, v58
	v_lshlrev_b32_e32 v58, 16, v59
	v_and_b32_e32 v59, 0xffff0000, v59
	s_waitcnt lgkmcnt(0)
	v_add_f32_e32 v66, v66, v68
	ds_bpermute_b32 v68, v115, v67
	v_lshlrev_b32_e32 v124, 16, v52
	v_and_b32_e32 v125, 0xffff0000, v52
	v_lshlrev_b32_e32 v52, 16, v53
	v_and_b32_e32 v53, 0xffff0000, v53
	s_waitcnt lgkmcnt(0)
	v_add_f32_e32 v67, v67, v68
	ds_bpermute_b32 v68, v115, v66
	v_lshlrev_b32_e32 v106, 16, v60
	v_and_b32_e32 v107, 0xffff0000, v60
	v_lshlrev_b32_e32 v60, 16, v61
	v_and_b32_e32 v61, 0xffff0000, v61
	s_waitcnt lgkmcnt(0)
	v_add_f32_e32 v66, v66, v68
	ds_bpermute_b32 v68, v120, v67
	v_lshlrev_b32_e32 v126, 16, v36
	v_and_b32_e32 v127, 0xffff0000, v36
	v_lshlrev_b32_e32 v36, 16, v37
	v_and_b32_e32 v37, 0xffff0000, v37
	s_waitcnt lgkmcnt(0)
	v_add_f32_e32 v67, v67, v68
	ds_bpermute_b32 v68, v120, v66
	s_waitcnt lgkmcnt(0)
	v_add_f32_e32 v66, v66, v68
	ds_bpermute_b32 v68, v121, v67
	s_waitcnt lgkmcnt(0)
	v_add_f32_e32 v67, v67, v68
	ds_bpermute_b32 v68, v121, v66
	v_fmamk_f32 v67, v67, 0x3a000000, v247
	v_rsq_f32_e32 v114, v67
	s_waitcnt lgkmcnt(0)
	v_add_f32_e32 v66, v66, v68
	v_fmamk_f32 v66, v66, 0x3a000000, v247
	v_rsq_f32_e32 v112, v66
	global_load_dwordx4 v[66:69], v[80:81], off offset:16
	global_load_dwordx4 v[116:119], v[80:81], off
	v_pk_mul_f32 v[50:51], v[114:115], v[50:51] op_sel_hi:[0,1]
	v_pk_mul_f32 v[122:123], v[114:115], v[122:123] op_sel_hi:[0,1]
	s_waitcnt vmcnt(0)
	v_pk_mul_f32 v[122:123], v[116:117], v[122:123]
	v_pk_mul_f32 v[50:51], v[118:119], v[50:51]
	v_pk_fma_f32 v[104:105], v[108:109], v[104:105], v[122:123] op_sel_hi:[0,1,1]
	v_pk_fma_f32 v[58:59], v[108:109], v[58:59], v[50:51] op_sel_hi:[0,1,1]
	v_pk_mul_f32 v[50:51], v[114:115], v[52:53] op_sel_hi:[0,1]
	v_pk_mul_f32 v[52:53], v[114:115], v[124:125] op_sel_hi:[0,1]
	v_lshlrev_b32_e32 v122, 16, v54
	v_and_b32_e32 v123, 0xffff0000, v54
	v_lshlrev_b32_e32 v54, 16, v55
	v_and_b32_e32 v55, 0xffff0000, v55
	v_pk_mul_f32 v[52:53], v[66:67], v[52:53]
	v_pk_mul_f32 v[50:51], v[68:69], v[50:51]
	v_pk_mul_f32 v[54:55], v[112:113], v[54:55] op_sel_hi:[0,1]
	v_pk_mul_f32 v[122:123], v[112:113], v[122:123] op_sel_hi:[0,1]
	v_pk_fma_f32 v[60:61], v[108:109], v[60:61], v[50:51] op_sel_hi:[0,1,1]
	v_pk_fma_f32 v[106:107], v[108:109], v[106:107], v[52:53] op_sel_hi:[0,1,1]
	v_lshlrev_b32_e32 v52, 16, v62
	v_and_b32_e32 v53, 0xffff0000, v62
	v_lshlrev_b32_e32 v50, 16, v63
	v_and_b32_e32 v51, 0xffff0000, v63
	v_lshlrev_b32_e32 v124, 16, v56
	v_and_b32_e32 v125, 0xffff0000, v56
	v_lshlrev_b32_e32 v56, 16, v57
	v_and_b32_e32 v57, 0xffff0000, v57
	v_pk_mul_f32 v[116:117], v[116:117], v[122:123]
	v_pk_mul_f32 v[54:55], v[118:119], v[54:55]
	v_lshlrev_b32_e32 v62, 16, v64
	v_pk_fma_f32 v[50:51], v[110:111], v[50:51], v[54:55] op_sel_hi:[0,1,1]
	v_pk_fma_f32 v[54:55], v[110:111], v[52:53], v[116:117] op_sel_hi:[0,1,1]
	v_pk_mul_f32 v[52:53], v[112:113], v[56:57] op_sel_hi:[0,1]
	v_pk_mul_f32 v[56:57], v[112:113], v[124:125] op_sel_hi:[0,1]
	global_load_dwordx4 v[116:119], v[80:81], off offset:2064
	global_load_dwordx4 v[122:125], v[80:81], off offset:2048
	v_and_b32_e32 v63, 0xffff0000, v64
	v_pk_mul_f32 v[56:57], v[66:67], v[56:57]
	v_lshlrev_b32_e32 v64, 16, v65
	v_pk_fma_f32 v[56:57], v[110:111], v[62:63], v[56:57] op_sel_hi:[0,1,1]
	v_lshlrev_b32_e32 v62, 16, v34
	v_and_b32_e32 v63, 0xffff0000, v34
	v_lshlrev_b32_e32 v34, 16, v35
	v_and_b32_e32 v35, 0xffff0000, v35
	v_and_b32_e32 v65, 0xffff0000, v65
	v_pk_mul_f32 v[52:53], v[68:69], v[52:53]
	v_pk_mul_f32 v[34:35], v[114:115], v[34:35] op_sel_hi:[0,1]
	v_pk_fma_f32 v[52:53], v[110:111], v[64:65], v[52:53] op_sel_hi:[0,1,1]
	v_lshlrev_b32_e32 v64, 16, v38
	v_and_b32_e32 v65, 0xffff0000, v38
	v_lshlrev_b32_e32 v38, 16, v39
	v_and_b32_e32 v39, 0xffff0000, v39
	v_pk_mul_f32 v[62:63], v[114:115], v[62:63] op_sel_hi:[0,1]
	v_lshlrev_b32_e32 v68, 16, v40
	v_and_b32_e32 v69, 0xffff0000, v40
	v_lshlrev_b32_e32 v40, 16, v41
	v_and_b32_e32 v41, 0xffff0000, v41
	s_waitcnt vmcnt(0)
; __device__ __forceinline__ void unpack8(u32x4 w, f32x4& a, f32x4& b) { a = (f32x4){bf_lo(w.x), bf_hi(w.x), bf_lo(w.y), bf_hi(w.y)}; b = (f32x4){bf_lo(w.z), bf_hi(w.z), bf_lo(w.w), bf_hi(w.w)}; }
; template <int NR>
; __device__ __forceinline__ void norm_prompt_rows(const Args& args, const float* gpost, bool last, bool want_q, const int (&rows)[NR], int lane) {
;     ...
; #pragma unroll
;     for (int j = 0; j < 4; ++j) {
;         const int c = j * 512 + lane * 8;
;         const f32x4 g0 = *(const f32x4*)(gpost + c), g1 = *(const f32x4*)(gpost + c + 4);
; #pragma unroll
;         for (int r = 0; r < NR; ++r) {
;             f32x4 x0, x1, y0, y1; unpack8(xq[r][j], x0, x1); unpack8(yq[r][j], y0, y1);
;             const f32x4 a = x0 * xs[r] + y0 * rstd[r] * g0, b = x1 * xs[r] + y1 * rstd[r] * g1;
;             n0[r][j] = a; n1[r][j] = b;
;             ss[r] += (a[0] * a[0] + a[1] * a[1]) + (a[2] * a[2] + a[3] * a[3]) + (b[0] * b[0] + b[1] * b[1]) + (b[2] * b[2] + b[3] * b[3]);
;         }
;     }
	v_pk_mul_f32 v[34:35], v[124:125], v[34:35]
	v_pk_mul_f32 v[66:67], v[122:123], v[62:63]
	v_pk_fma_f32 v[62:63], v[108:109], v[38:39], v[34:35] op_sel_hi:[0,1,1]
	v_pk_mul_f32 v[34:35], v[114:115], v[36:37] op_sel_hi:[0,1]
	v_pk_mul_f32 v[36:37], v[114:115], v[126:127] op_sel_hi:[0,1]
	v_lshlrev_b32_e32 v38, 16, v42
	v_and_b32_e32 v39, 0xffff0000, v42
	v_lshlrev_b32_e32 v42, 16, v43
	v_and_b32_e32 v43, 0xffff0000, v43
	v_pk_mul_f32 v[36:37], v[116:117], v[36:37]
	v_pk_mul_f32 v[34:35], v[118:119], v[34:35]
	v_pk_mul_f32 v[42:43], v[112:113], v[42:43] op_sel_hi:[0,1]
	v_pk_mul_f32 v[38:39], v[112:113], v[38:39] op_sel_hi:[0,1]
	v_pk_fma_f32 v[66:67], v[108:109], v[64:65], v[66:67] op_sel_hi:[0,1,1]
	v_pk_fma_f32 v[64:65], v[108:109], v[40:41], v[34:35] op_sel_hi:[0,1,1]
	v_pk_fma_f32 v[68:69], v[108:109], v[68:69], v[36:37] op_sel_hi:[0,1,1]
	v_lshlrev_b32_e32 v34, 16, v46
	v_and_b32_e32 v35, 0xffff0000, v46
	v_lshlrev_b32_e32 v36, 16, v47
	v_and_b32_e32 v37, 0xffff0000, v47
	v_lshlrev_b32_e32 v46, 16, v48
	v_and_b32_e32 v47, 0xffff0000, v48
	v_lshlrev_b32_e32 v40, 16, v49
	v_and_b32_e32 v41, 0xffff0000, v49
	v_lshlrev_b32_e32 v48, 16, v44
	v_and_b32_e32 v49, 0xffff0000, v44
	v_lshlrev_b32_e32 v44, 16, v45
	v_and_b32_e32 v45, 0xffff0000, v45
	v_pk_mul_f32 v[122:123], v[122:123], v[38:39]
	v_pk_mul_f32 v[38:39], v[124:125], v[42:43]
	v_pk_fma_f32 v[42:43], v[110:111], v[34:35], v[122:123] op_sel_hi:[0,1,1]
	v_pk_fma_f32 v[38:39], v[110:111], v[36:37], v[38:39] op_sel_hi:[0,1,1]
	v_pk_mul_f32 v[34:35], v[112:113], v[44:45] op_sel_hi:[0,1]
	v_pk_mul_f32 v[36:37], v[112:113], v[48:49] op_sel_hi:[0,1]
	v_pk_mul_f32 v[36:37], v[116:117], v[36:37]
	v_pk_mul_f32 v[34:35], v[118:119], v[34:35]
	v_pk_fma_f32 v[44:45], v[110:111], v[46:47], v[36:37] op_sel_hi:[0,1,1]
	v_pk_fma_f32 v[40:41], v[110:111], v[40:41], v[34:35] op_sel_hi:[0,1,1]
	global_load_dwordx4 v[34:37], v[82:83], off offset:16
	global_load_dwordx4 v[122:125], v[82:83], off
	v_lshlrev_b32_e32 v46, 16, v18
	v_and_b32_e32 v47, 0xffff0000, v18
	v_lshlrev_b32_e32 v18, 16, v19
	v_and_b32_e32 v19, 0xffff0000, v19
	v_pk_mul_f32 v[18:19], v[114:115], v[18:19] op_sel_hi:[0,1]
	v_lshlrev_b32_e32 v48, 16, v22
	v_and_b32_e32 v49, 0xffff0000, v22
	v_lshlrev_b32_e32 v22, 16, v23
	v_and_b32_e32 v23, 0xffff0000, v23
	v_lshlrev_b32_e32 v126, 16, v20
	v_and_b32_e32 v127, 0xffff0000, v20
	v_lshlrev_b32_e32 v20, 16, v21
	v_and_b32_e32 v21, 0xffff0000, v21
	v_pk_mul_f32 v[46:47], v[114:115], v[46:47] op_sel_hi:[0,1]
	v_lshlrev_b32_e32 v118, 16, v24
	v_and_b32_e32 v119, 0xffff0000, v24
	v_lshlrev_b32_e32 v24, 16, v25
	v_and_b32_e32 v25, 0xffff0000, v25
	s_waitcnt vmcnt(0)
	v_pk_mul_f32 v[18:19], v[124:125], v[18:19]
	v_pk_mul_f32 v[116:117], v[122:123], v[46:47]
	v_pk_fma_f32 v[46:47], v[108:109], v[22:23], v[18:19] op_sel_hi:[0,1,1]
	v_pk_mul_f32 v[18:19], v[114:115], v[20:21] op_sel_hi:[0,1]
	v_pk_mul_f32 v[20:21], v[114:115], v[126:127] op_sel_hi:[0,1]
	v_pk_mul_f32 v[20:21], v[34:35], v[20:21]
	v_pk_mul_f32 v[18:19], v[36:37], v[18:19]
	v_pk_fma_f32 v[116:117], v[108:109], v[48:49], v[116:117] op_sel_hi:[0,1,1]
	v_pk_fma_f32 v[48:49], v[108:109], v[24:25], v[18:19] op_sel_hi:[0,1,1]
	v_pk_fma_f32 v[118:119], v[108:109], v[118:119], v[20:21] op_sel_hi:[0,1,1]
	v_lshlrev_b32_e32 v18, 16, v30
	v_and_b32_e32 v19, 0xffff0000, v30
	v_lshlrev_b32_e32 v20, 16, v31
	v_and_b32_e32 v21, 0xffff0000, v31
	v_lshlrev_b32_e32 v30, 16, v26
	v_and_b32_e32 v31, 0xffff0000, v26
	v_lshlrev_b32_e32 v26, 16, v27
	v_and_b32_e32 v27, 0xffff0000, v27
	v_pk_mul_f32 v[26:27], v[112:113], v[26:27] op_sel_hi:[0,1]
	v_pk_mul_f32 v[30:31], v[112:113], v[30:31] op_sel_hi:[0,1]
	v_lshlrev_b32_e32 v22, 16, v32
	v_and_b32_e32 v23, 0xffff0000, v32
	v_lshlrev_b32_e32 v24, 16, v33
	v_and_b32_e32 v25, 0xffff0000, v33
	v_lshlrev_b32_e32 v32, 16, v28
	v_and_b32_e32 v33, 0xffff0000, v28
	v_lshlrev_b32_e32 v28, 16, v29
	v_and_b32_e32 v29, 0xffff0000, v29
	v_pk_mul_f32 v[30:31], v[122:123], v[30:31]
	v_pk_mul_f32 v[26:27], v[124:125], v[26:27]
	v_pk_fma_f32 v[30:31], v[110:111], v[18:19], v[30:31] op_sel_hi:[0,1,1]
	v_pk_fma_f32 v[26:27], v[110:111], v[20:21], v[26:27] op_sel_hi:[0,1,1]
	v_pk_mul_f32 v[18:19], v[112:113], v[28:29] op_sel_hi:[0,1]
	v_pk_mul_f32 v[20:21], v[112:113], v[32:33] op_sel_hi:[0,1]
	v_pk_mul_f32 v[20:21], v[34:35], v[20:21]
	v_pk_mul_f32 v[18:19], v[36:37], v[18:19]
	v_pk_fma_f32 v[32:33], v[110:111], v[22:23], v[20:21] op_sel_hi:[0,1,1]
	v_pk_fma_f32 v[28:29], v[110:111], v[24:25], v[18:19] op_sel_hi:[0,1,1]
	global_load_dwordx4 v[18:21], v[84:85], off offset:16
	global_load_dwordx4 v[22:25], v[84:85], off
	v_lshlrev_b32_e32 v122, 16, v16
	v_and_b32_e32 v123, 0xffff0000, v16
	v_lshlrev_b32_e32 v124, 16, v17
	v_and_b32_e32 v125, 0xffff0000, v17
	v_lshlrev_b32_e32 v16, 16, v12
	v_and_b32_e32 v17, 0xffff0000, v12
	v_pk_mul_f32 v[16:17], v[114:115], v[16:17] op_sel_hi:[0,1]
	v_lshlrev_b32_e32 v34, 16, v14
	v_and_b32_e32 v35, 0xffff0000, v14
	v_lshlrev_b32_e32 v36, 16, v15
	v_and_b32_e32 v37, 0xffff0000, v15
	v_lshlrev_b32_e32 v14, 16, v10
	v_and_b32_e32 v15, 0xffff0000, v10
	v_lshlrev_b32_e32 v12, 16, v13
	v_and_b32_e32 v13, 0xffff0000, v13
	v_pk_mul_f32 v[14:15], v[114:115], v[14:15] op_sel_hi:[0,1]
	v_pk_mul_f32 v[12:13], v[114:115], v[12:13] op_sel_hi:[0,1]
	v_lshlrev_b32_e32 v10, 16, v11
	v_and_b32_e32 v11, 0xffff0000, v11
	v_pk_mul_f32 v[10:11], v[114:115], v[10:11] op_sel_hi:[0,1]
	s_waitcnt vmcnt(1)
	v_pk_mul_f32 v[16:17], v[16:17], v[18:19]
	s_nop 0
	v_pk_fma_f32 v[16:17], v[108:109], v[122:123], v[16:17] op_sel_hi:[0,1,1]
	v_lshlrev_b32_e32 v122, 16, v2
	v_and_b32_e32 v123, 0xffff0000, v2
	v_lshlrev_b32_e32 v2, 16, v3
	v_and_b32_e32 v3, 0xffff0000, v3
	s_waitcnt vmcnt(0)
; __device__ __forceinline__ void unpack8(u32x4 w, f32x4& a, f32x4& b) { a = (f32x4){bf_lo(w.x), bf_hi(w.x), bf_lo(w.y), bf_hi(w.y)}; b = (f32x4){bf_lo(w.z), bf_hi(w.z), bf_lo(w.w), bf_hi(w.w)}; }
; template <int NR>
; __device__ __forceinline__ void norm_prompt_rows(const Args& args, const float* gpost, bool last, bool want_q, const int (&rows)[NR], int lane) {
;     ...
;     for (int j = 0; j < 4; ++j) {
;         const int c = j * 512 + lane * 8;
;         const f32x4 g0 = *(const f32x4*)(gpost + c), g1 = *(const f32x4*)(gpost + c + 4);
; #pragma unroll
;         for (int r = 0; r < NR; ++r) {
;             f32x4 x0, x1, y0, y1; unpack8(xq[r][j], x0, x1); unpack8(yq[r][j], y0, y1);
;             const f32x4 a = x0 * xs[r] + y0 * rstd[r] * g0, b = x1 * xs[r] + y1 * rstd[r] * g1;
;             n0[r][j] = a; n1[r][j] = b;
;             ss[r] += (a[0] * a[0] + a[1] * a[1]) + (a[2] * a[2] + a[3] * a[3]) + (b[0] * b[0] + b[1] * b[1]) + (b[2] * b[2] + b[3] * b[3]);
;         }
;     }
;     if (last) {
; #pragma unroll
;         for (int r = 0; r < NR; ++r) { float* xo = args.out + (size_t)rows[r] * DM;
; #pragma unroll
;             for (int j = 0; j < 4; ++j) { *(f32x4*)(xo + j * 512 + lane * 8) = n0[r][j]; *(f32x4*)(xo + j * 512 + lane * 8 + 4) = n1[r][j]; } }
;     } else {
; #pragma unroll
;         for (int o = 1; o < 64; o <<= 1)
; #pragma unroll
;             for (int r = 0; r < NR; ++r) ss[r] += __shfl_xor(ss[r], o);
	v_pk_mul_f32 v[14:15], v[22:23], v[14:15]
	v_pk_mul_f32 v[12:13], v[12:13], v[20:21]
	v_pk_mul_f32 v[2:3], v[112:113], v[2:3] op_sel_hi:[0,1]
	v_pk_mul_f32 v[122:123], v[112:113], v[122:123] op_sel_hi:[0,1]
	v_pk_fma_f32 v[14:15], v[108:109], v[34:35], v[14:15] op_sel_hi:[0,1,1]
	v_pk_fma_f32 v[12:13], v[108:109], v[124:125], v[12:13] op_sel_hi:[0,1,1]
	v_lshlrev_b32_e32 v34, 16, v6
	v_and_b32_e32 v35, 0xffff0000, v6
	v_lshlrev_b32_e32 v6, 16, v7
	v_and_b32_e32 v7, 0xffff0000, v7
	v_lshlrev_b32_e32 v124, 16, v4
	v_and_b32_e32 v125, 0xffff0000, v4
	v_lshlrev_b32_e32 v4, 16, v5
	v_and_b32_e32 v5, 0xffff0000, v5
	v_pk_mul_f32 v[22:23], v[22:23], v[122:123]
	v_pk_mul_f32 v[2:3], v[24:25], v[2:3]
	v_pk_mul_f32 v[10:11], v[24:25], v[10:11]
	v_pk_fma_f32 v[2:3], v[110:111], v[6:7], v[2:3] op_sel_hi:[0,1,1]
	v_pk_fma_f32 v[6:7], v[110:111], v[34:35], v[22:23] op_sel_hi:[0,1,1]
	v_pk_mul_f32 v[4:5], v[112:113], v[4:5] op_sel_hi:[0,1]
	v_pk_mul_f32 v[22:23], v[112:113], v[124:125] op_sel_hi:[0,1]
	v_pk_fma_f32 v[10:11], v[108:109], v[36:37], v[10:11] op_sel_hi:[0,1,1]
	v_lshlrev_b32_e32 v36, 16, v8
	v_and_b32_e32 v37, 0xffff0000, v8
	v_lshlrev_b32_e32 v8, 16, v9
	v_and_b32_e32 v9, 0xffff0000, v9
	v_pk_mul_f32 v[18:19], v[18:19], v[22:23]
	v_pk_mul_f32 v[4:5], v[20:21], v[4:5]
	v_mul_f32_e32 v20, v55, v55
	v_mul_f32_e32 v21, v51, v51
	v_pk_fma_f32 v[4:5], v[110:111], v[8:9], v[4:5] op_sel_hi:[0,1,1]
	v_pk_fma_f32 v[8:9], v[110:111], v[36:37], v[18:19] op_sel_hi:[0,1,1]
	v_mul_f32_e32 v19, v57, v57
	v_fmac_f32_e32 v20, v54, v54
	v_fmac_f32_e32 v21, v50, v50
	v_mul_f32_e32 v18, v53, v53
	v_fmac_f32_e32 v19, v56, v56
	v_add_f32_e32 v20, v20, v21
	v_mul_f32_e32 v21, v43, v43
	v_mul_f32_e32 v22, v39, v39
	v_fmac_f32_e32 v18, v52, v52
	v_add_f32_e32 v19, v19, v20
	v_mul_f32_e32 v20, v45, v45
	v_fmac_f32_e32 v21, v42, v42
	v_fmac_f32_e32 v22, v38, v38
	v_add_f32_e32 v18, v18, v19
	v_mul_f32_e32 v19, v41, v41
	v_fmac_f32_e32 v20, v44, v44
	v_add_f32_e32 v21, v21, v22
	v_fmac_f32_e32 v19, v40, v40
	v_add_f32_e32 v20, v20, v21
	v_mul_f32_e32 v21, v31, v31
	v_mul_f32_e32 v22, v27, v27
	v_add_f32_e32 v19, v19, v20
	v_mul_f32_e32 v20, v33, v33
	v_fmac_f32_e32 v21, v30, v30
	v_fmac_f32_e32 v22, v26, v26
	v_add_f32_e32 v18, v18, v19
	v_mul_f32_e32 v19, v29, v29
	v_fmac_f32_e32 v20, v32, v32
	v_add_f32_e32 v21, v21, v22
	v_fmac_f32_e32 v19, v28, v28
	v_add_f32_e32 v20, v20, v21
	v_mul_f32_e32 v21, v7, v7
	v_mul_f32_e32 v22, v3, v3
	v_add_f32_e32 v19, v19, v20
	v_mul_f32_e32 v20, v9, v9
	v_fmac_f32_e32 v21, v6, v6
	v_fmac_f32_e32 v22, v2, v2
	v_add_f32_e32 v18, v19, v18
	v_mul_f32_e32 v19, v5, v5
	v_fmac_f32_e32 v20, v8, v8
	v_add_f32_e32 v21, v21, v22
	v_fmac_f32_e32 v19, v4, v4
	v_add_f32_e32 v20, v20, v21
	v_add_f32_e32 v19, v19, v20
	v_add_f32_e32 v108, v19, v18
	v_pk_mul_f32 v[18:19], v[60:61], v[60:61]
	v_pk_mul_f32 v[20:21], v[106:107], v[106:107]
	v_mov_b32_e32 v22, v18
	v_mov_b32_e32 v23, v20
	v_mov_b32_e32 v20, v19
	v_pk_add_f32 v[18:19], v[22:23], v[20:21]
	v_pk_mul_f32 v[20:21], v[58:59], v[58:59]
	v_pk_mul_f32 v[22:23], v[104:105], v[104:105]
	v_mul_f32_e32 v36, v13, v13
	v_pk_mov_b32 v[24:25], v[22:23], v[20:21] op_sel:[1,0]
	v_mov_b32_e32 v23, v21
	v_pk_add_f32 v[20:21], v[24:25], v[22:23]
	v_pk_mul_f32 v[22:23], v[68:69], v[68:69]
	v_pk_add_f32 v[20:21], v[20:21], v[20:21] op_sel:[0,1] op_sel_hi:[1,0]
	v_mov_b32_e32 v25, v22
	v_pk_add_f32 v[20:21], v[18:19], v[20:21] op_sel:[1,0] op_sel_hi:[0,1]
	v_pk_add_f32 v[18:19], v[18:19], v[20:21]
	v_pk_mul_f32 v[20:21], v[64:65], v[64:65]
	s_nop 0
	v_mov_b32_e32 v24, v20
	v_mov_b32_e32 v22, v21
	v_pk_add_f32 v[20:21], v[24:25], v[22:23]
	v_pk_mul_f32 v[22:23], v[62:63], v[62:63]
	v_pk_mul_f32 v[24:25], v[66:67], v[66:67]
	s_nop 0
	v_pk_mov_b32 v[34:35], v[24:25], v[22:23] op_sel:[1,0]
	v_mov_b32_e32 v25, v23
	v_pk_add_f32 v[22:23], v[34:35], v[24:25]
	v_mul_f32_e32 v34, v12, v12
	v_pk_add_f32 v[22:23], v[22:23], v[22:23] op_sel:[0,1] op_sel_hi:[1,0]
	v_mov_b32_e32 v35, v18
	v_pk_add_f32 v[22:23], v[20:21], v[22:23] op_sel:[1,0] op_sel_hi:[0,1]
	v_pk_add_f32 v[20:21], v[20:21], v[22:23]
	v_mul_f32_e32 v22, v116, v116
	v_pk_fma_f32 v[22:23], v[116:117], v[116:117], v[22:23] op_sel_hi:[1,1,0]
	v_mov_b32_e32 v37, v20
	v_mul_f32_e32 v22, v46, v46
	v_pk_add_f32 v[18:19], v[34:35], v[36:37]
	v_mov_b32_e32 v34, v17
	v_mov_b32_e32 v35, v49
	v_pk_fma_f32 v[24:25], v[46:47], v[46:47], v[22:23] op_sel_hi:[1,1,0]
	v_mov_b32_e32 v20, v16
	v_mov_b32_e32 v21, v48
	v_pk_mul_f32 v[34:35], v[34:35], v[34:35]
	v_mov_b32_e32 v36, v15
	v_mov_b32_e32 v37, v119
	v_mul_f32_e32 v22, v10, v10
	v_mul_f32_e32 v24, v11, v11
	v_pk_fma_f32 v[20:21], v[20:21], v[20:21], v[34:35]
	v_mov_b32_e32 v34, v14
	v_mov_b32_e32 v35, v118
	v_pk_mul_f32 v[36:37], v[36:37], v[36:37]
	v_pk_add_f32 v[22:23], v[22:23], v[24:25]
	v_pk_fma_f32 v[34:35], v[34:35], v[34:35], v[36:37]
	s_nop 0
	v_pk_add_f32 v[22:23], v[34:35], v[22:23]
	s_nop 0
	v_pk_add_f32 v[20:21], v[20:21], v[22:23]
	s_nop 0
	v_pk_add_f32 v[18:19], v[20:21], v[18:19]
	s_nop 0
	v_add_f32_e32 v18, v18, v19
	ds_bpermute_b32 v19, v109, v18
	s_waitcnt lgkmcnt(0)
; __device__ __forceinline__ u32x4 pack8(f32x4 a, f32x4 b) { u32x4 w; w.x = cvtpk(a[0], a[1]); w.y = cvtpk(a[2], a[3]); w.z = cvtpk(b[0], b[1]); w.w = cvtpk(b[2], b[3]); return w; }
; template <int NR>
; __device__ __forceinline__ void norm_prompt_rows(const Args& args, const float* gpost, bool last, bool want_q, const int (&rows)[NR], int lane) {
;     ...
; #pragma unroll
;         for (int o = 1; o < 64; o <<= 1)
; #pragma unroll
;             for (int r = 0; r < NR; ++r) ss[r] += __shfl_xor(ss[r], o);
; #pragma unroll
;         for (int r = 0; r < NR; ++r) {
;             const float ms = ss[r] * (1.0f / DM) + EPS, rs2 = __builtin_amdgcn_rsqf(ms);
; #pragma unroll
;             for (int j = 0; j < 4; ++j) *(u32x4*)(XB + (size_t)rows[r] * DM + j * 512 + lane * 8) = pack8(n0[r][j] * rs2, n1[r][j] * rs2);
;             if (lane == 0) RS[rows[r]] = __builtin_sqrtf(ms);
	v_add_f32_e32 v18, v18, v19
	ds_bpermute_b32 v19, v109, v108
	ds_bpermute_b32 v20, v111, v18
	s_waitcnt lgkmcnt(1)
	v_add_f32_e32 v19, v108, v19
	s_waitcnt lgkmcnt(0)
	v_add_f32_e32 v18, v18, v20
	ds_bpermute_b32 v20, v111, v19
	s_waitcnt lgkmcnt(0)
	v_add_f32_e32 v19, v19, v20
	ds_bpermute_b32 v20, v113, v18
	s_waitcnt lgkmcnt(0)
	v_add_f32_e32 v18, v18, v20
	ds_bpermute_b32 v20, v113, v19
	s_waitcnt lgkmcnt(0)
	v_add_f32_e32 v19, v19, v20
	ds_bpermute_b32 v20, v115, v18
	s_waitcnt lgkmcnt(0)
	v_add_f32_e32 v18, v18, v20
	ds_bpermute_b32 v20, v115, v19
	s_waitcnt lgkmcnt(0)
	v_add_f32_e32 v19, v19, v20
	ds_bpermute_b32 v20, v120, v18
	s_waitcnt lgkmcnt(0)
	v_add_f32_e32 v18, v18, v20
	ds_bpermute_b32 v20, v120, v19
	s_waitcnt lgkmcnt(0)
	v_add_f32_e32 v19, v19, v20
	ds_bpermute_b32 v20, v121, v18
	s_waitcnt lgkmcnt(0)
	v_add_f32_e32 v18, v18, v20
	v_fmamk_f32 v21, v18, 0x3a000000, v247
	v_rsq_f32_e32 v18, v21
	ds_bpermute_b32 v20, v121, v19
	v_pk_mul_f32 v[24:25], v[58:59], v[18:19] op_sel_hi:[1,0]
	v_pk_mul_f32 v[22:23], v[104:105], v[18:19] op_sel_hi:[1,0]
	v_pk_mul_f32 v[34:35], v[60:61], v[18:19] op_sel_hi:[1,0]
	v_pk_mul_f32 v[36:37], v[106:107], v[18:19] op_sel_hi:[1,0]
	v_cvt_pk_bf16_f32 v22, v22, v23
	v_cvt_pk_bf16_f32 v23, v24, v25
	v_cvt_pk_bf16_f32 v24, v36, v37
	v_cvt_pk_bf16_f32 v25, v34, v35
	global_store_dwordx4 v[102:103], v[22:25], off
	v_pk_mul_f32 v[34:35], v[64:65], v[18:19] op_sel_hi:[1,0]
	v_pk_mul_f32 v[36:37], v[68:69], v[18:19] op_sel_hi:[1,0]
	v_pk_mul_f32 v[24:25], v[62:63], v[18:19] op_sel_hi:[1,0]
	v_pk_mul_f32 v[22:23], v[66:67], v[18:19] op_sel_hi:[1,0]
	s_nop 0
	v_cvt_pk_bf16_f32 v22, v22, v23
	v_cvt_pk_bf16_f32 v23, v24, v25
	v_cvt_pk_bf16_f32 v24, v36, v37
	v_cvt_pk_bf16_f32 v25, v34, v35
	global_store_dwordx4 v[100:101], v[22:25], off
	v_pk_mul_f32 v[34:35], v[48:49], v[18:19] op_sel_hi:[1,0]
	v_pk_mul_f32 v[36:37], v[118:119], v[18:19] op_sel_hi:[1,0]
	v_pk_mul_f32 v[24:25], v[46:47], v[18:19] op_sel_hi:[1,0]
	v_pk_mul_f32 v[22:23], v[116:117], v[18:19] op_sel_hi:[1,0]
	s_nop 0
	v_cvt_pk_bf16_f32 v22, v22, v23
	v_cvt_pk_bf16_f32 v23, v24, v25
	v_cvt_pk_bf16_f32 v24, v36, v37
	v_cvt_pk_bf16_f32 v25, v34, v35
	global_store_dwordx4 v[98:99], v[22:25], off
	v_pk_mul_f32 v[34:35], v[12:13], v[18:19] op_sel_hi:[1,0]
	v_pk_mul_f32 v[36:37], v[16:17], v[18:19] op_sel_hi:[1,0]
	v_pk_mul_f32 v[24:25], v[10:11], v[18:19] op_sel_hi:[1,0]
	v_pk_mul_f32 v[22:23], v[14:15], v[18:19] op_sel_hi:[1,0]
	s_nop 0
	v_cvt_pk_bf16_f32 v22, v22, v23
	v_cvt_pk_bf16_f32 v23, v24, v25
	v_cvt_pk_bf16_f32 v24, v36, v37
	v_cvt_pk_bf16_f32 v25, v34, v35
	global_store_dwordx4 v[96:97], v[22:25], off
	s_and_saveexec_b64 s[42:43], s[54:55]
	s_cbranch_execz .LBB0_1246
	s_mov_b32 s2, 0xf800000
	v_mul_f32_e32 v22, 0x4f800000, v21
	v_cmp_gt_f32_e32 vcc, s2, v21
	s_nop 1
	v_cndmask_b32_e32 v21, v21, v22, vcc
	v_sqrt_f32_e32 v22, v21
	s_nop 0
	v_add_u32_e32 v23, -1, v22
	v_fma_f32 v25, -v23, v22, v21
	v_add_u32_e32 v24, 1, v22
	v_cmp_ge_f32_e64 s[56:57], 0, v25
	s_nop 1
	v_cndmask_b32_e64 v23, v22, v23, s[56:57]
	v_fma_f32 v22, -v24, v22, v21
	v_cmp_lt_f32_e64 s[56:57], 0, v22
	s_nop 1
	v_cndmask_b32_e64 v22, v23, v24, s[56:57]
	v_mul_f32_e32 v23, 0x37800000, v22
	v_cndmask_b32_e32 v22, v22, v23, vcc
	v_cmp_class_f32_e32 vcc, v21, v245
	s_nop 1
	v_cndmask_b32_e32 v21, v22, v21, vcc
	global_store_dword v131, v21, s[40:41]
